# N2 step top: next-step selection + K/V tile base addresses on the scalar unit, saddr tile loads issued before the second barrier
# speedup vs baseline: 1.0353x; 1.0095x over previous
; __device__ void phaseN2_task(const Params& p, int task, char* lds, bf16_t* ydst, int ystride, volatile unsigned* uex, char* ldsb) {
;     ...
;     {
;         const int lo = (t0 & ~31) - 511;
;         const int jb0 = lo > 0 ? (lo >> 6) : 0;
;         const int kkey = t512 >> 3, kch = (t512 & 7) * 8;
;         const int vd = t512 >> 3, vch = (t512 & 7) * 8;
;         const bf16_t* vtb = (const bf16_t*)(p.ws + OFF_VT) + ((size_t)(b * 2 + g) * 64 + vd) * SEQ + vch;
;         u32x4 kreg, vreg;
;         int br = 0, j = 0;
;         {
;             const bf16_t* kb = Z + (rowb + 0) * ZC + ZKS + g * 64;
;             kreg = *(const u32x4*)(kb + (size_t)kkey * ZC + kch);
;             vreg = *(const u32x4*)(vtb);
;         }
;         f32x4 O[2][4];
;         float m[2] = {-1e30f, -1e30f}, l[2] = {0.f, 0.f};
; #pragma unroll
;         for (int x = 0; x < 2; x++)
; #pragma unroll
;             for (int dt = 0; dt < 4; dt++) O[x][dt] = (f32x4){0.f, 0.f, 0.f, 0.f};
;         for (;;) {
;             __syncthreads();
;             *(u32x4*)(Ks + kkey * 64 + (((kch >> 3) ^ (kkey & 7)) * 8)) = kreg;
;             *(u32x4*)(VT + vd * 72 + vch) = vreg;
;             __syncthreads();
;             int nbr, nj;
;             if (br == 0) {
;                 const unsigned rem = (j >= 31) ? 0u : (uni & ~((2u << j) - 1u));
;                 if (rem) { nbr = 0; nj = __ffs((int)rem) - 1; } else { nbr = 1; nj = jb0; }
;             } else {
;                 if (j < cur) { nbr = 1; nj = j + 1; } else { nbr = 2; nj = 0; }
;             }
;             if (nbr < 2) {
;                 const bf16_t* kb = Z + (rowb + nj * 64) * ZC + (nbr ? ZKW : ZKS) + g * 64;
;                 kreg = *(const u32x4*)(kb + (size_t)kkey * ZC + kch);
;                 vreg = *(const u32x4*)(vtb + (size_t)nbr * (8 * 2 * 64) * SEQ + nj * 64);
;             }
;             int klo = 0, khi = -1;
;             if (br == 0) { if ((mysel >> j) & 1u) khi = t - j * 64; }
;             else { khi = t - j * 64; klo = t - 511 - j * 64; }
;             klo = klo < 0 ? 0 : klo;
;             khi = khi > 63 ? 63 : khi;
.LBB0_616:
	s_or_b64 exec, exec, s[4:5]
	s_lshl_b32 s4, 2, s76
	s_add_i32 s4, s4, -1
	s_cmp_lg_u32 s76, 31
	s_cselect_b32 s10, s4, -2
	s_add_i32 s4, s1, 0xfffffe01
	s_ashr_i32 s11, s4, 6
	s_lshl_b32 s0, s0, 18
	s_add_u32 s4, s92, s0
	v_ashrrev_i32_e32 v49, 31, v48
	s_addc_u32 s5, s93, 0
	s_mul_i32 s0, s88, 0x2700
	v_lshlrev_b64 v[16:17], 12, v[48:49]
	s_add_u32 s0, s90, s0
	v_lshlrev_b32_e32 v25, 3, v124
	v_lshl_add_u64 v[16:17], s[4:5], 0, v[16:17]
	s_addc_u32 s5, s91, 0
	s_lshl_b32 s12, s89, 6
	s_lshl_b32 s4, s89, 7
	v_and_b32_e32 v34, 56, v25
	s_add_u32 s4, s0, s4
	s_movk_i32 s0, 0x1380
	v_lshlrev_b32_e32 v88, 1, v34
	s_addc_u32 s5, s5, 0
	v_mad_i64_i32 v[94:95], s[6:7], v48, s0, 0
	v_lshl_add_u64 v[36:37], v[16:17], 0, v[88:89]
	v_lshl_add_u64 v[16:17], v[94:95], 1, s[4:5]
	v_lshl_add_u64 v[16:17], v[16:17], 0, v[88:89]
	s_movk_i32 s0, 0x2000
	v_add_co_u32_e32 v16, vcc, s0, v16
	s_mov_b32 s0, 0xf800000
	s_nop 0
	v_addc_co_u32_e32 v17, vcc, 0, v17, vcc
	v_mov_b32_e32 v93, v91
	v_add_co_u32_e32 v20, vcc, s0, v36
	s_waitcnt lgkmcnt(0)
	s_barrier
	flat_load_dword v33, v[90:91] sc0 sc1
	s_waitcnt vmcnt(0)
	flat_load_dword v35, v[92:93] sc0 sc1
	s_waitcnt vmcnt(0)
	v_addc_co_u32_e32 v21, vcc, 0, v37, vcc
	global_load_dwordx4 v[16:19], v[16:17], off offset:512
	s_nop 0
	global_load_dwordx4 v[20:23], v[20:21], off
	v_and_b32_e32 v26, 7, v124
	v_lshlrev_b32_e32 v38, 7, v48
	v_bitop3_b32 v27, v75, v124, 7 bitop3:0x78
	v_bitop3_b32 v40, v25, 56, v124 bitop3:0x48
	v_bitop3_b32 v42, v75, v26, 4 bitop3:0x36
	v_lshlrev_b32_e32 v39, 4, v48
	v_lshlrev_b32_e32 v28, 4, v74
	v_lshlrev_b32_e32 v29, 1, v129
	v_mov_b32_e32 v24, 0
	v_lshlrev_b32_e32 v41, 4, v27
	v_lshl_or_b32 v136, v40, 1, v38
	v_lshlrev_b32_e32 v40, 4, v42
	s_mov_b64 s[4:5], 0xf800000
	s_cmpk_gt_i32 s1, 0x1ff
	s_mov_b32 s89, s85
	v_lshrrev_b32_e32 v93, 16, v127
	v_lshrrev_b32_e32 v133, 16, v128
	v_add_u32_e32 v134, 0xfffffe01, v126
	v_mov_b32_e32 v143, 0
	v_mov_b32_e32 v102, 0xf149f2ca
	s_mov_b64 s[8:9], 0
	v_mov_b32_e32 v103, 0xf149f2ca
	v_mov_b32_e32 v56, 0
	v_add3_u32 v135, v51, v28, v29
	v_mov_b32_e32 v25, v24
	v_mov_b32_e32 v26, v24
	v_mov_b32_e32 v27, v24
	v_mov_b32_e32 v28, v24
	v_mov_b32_e32 v29, v24
	v_mov_b32_e32 v30, v24
	v_mov_b32_e32 v31, v24
	v_mov_b32_e32 v32, v24
	v_lshlrev_b32_e32 v96, 1, v34
	v_add_u32_e32 v137, v51, v41
	v_add3_u32 v138, v38, v39, v88
	v_add_u32_e32 v139, v51, v40
	v_lshl_add_u64 v[98:99], v[36:37], 0, s[4:5]
	s_cselect_b32 s0, s11, 0
	s_lshl_b32 s84, s12, 1
	v_mov_b32_e32 v34, v24
	v_mov_b32_e32 v36, v24
	v_mov_b32_e32 v37, v24
	v_mov_b32_e32 v38, v24
	v_mov_b32_e32 v39, v24
	v_mov_b32_e32 v40, v24
	v_mov_b32_e32 v41, v24
	v_mov_b32_e32 v42, v24
	v_mov_b32_e32 v43, v24
	v_mov_b32_e32 v44, v24
	v_mov_b32_e32 v45, v24
	v_mov_b32_e32 v46, v24
	v_mov_b32_e32 v47, v24
	v_mov_b32_e32 v48, v24
	v_mov_b32_e32 v49, v24
	v_mov_b32_e32 v50, v24
	v_mov_b32_e32 v51, v24
	v_mov_b32_e32 v52, v24
	v_mov_b32_e32 v53, v24
	v_mov_b32_e32 v54, v24
	v_mov_b32_e32 v55, v24
	v_mov_b32_e32 v100, v24
	v_mov_b32_e32 v101, v24
	s_waitcnt lgkmcnt(0)
	v_bitop3_b32 v140, v35, s10, v33 bitop3:0xc8
	v_mov_b32_e32 v33, v24
	v_mov_b32_e32 v35, v24
	v_mov_b32_e32 v176, 0
	v_mov_b32_e32 v177, 0
	v_mov_b32_e32 v178, v123
	v_mov_b32_e32 v179, v123
	s_mov_b32 s34, 0
	s_mov_b32 s35, 0
	v_lshl_add_u32 v183, v94, 1, v96
	v_readfirstlane_b32 s56, v98
	v_readfirstlane_b32 s57, v99
	v_readfirstlane_b32 s54, v140
	s_nop 1
	v_subrev_u32_e32 v163, s56, v98
	s_branch .LBB0_618
.LBB0_617:
	s_or_b64 exec, exec, s[6:7]
	v_cmp_eq_u32_e32 vcc, 2, v141
	s_or_b64 s[8:9], vcc, s[8:9]
	v_mov_b32_e32 v102, v97
	v_mov_b32_e32 v103, v88
	v_mov_b32_e32 v143, v141
	s_mov_b32 s34, s52
	s_mov_b32 s35, s51
	s_andn2_b64 exec, exec, s[8:9]
	s_cbranch_execz .LBB0_593
	.p2alignl 6, 3212836864
.LBB0_618:
	s_cmp_eq_u32 s34, 0
	s_cselect_b64 s[4:5], -1, 0
	s_cbranch_scc0 .Ln2_t_win
	s_lshl_b32 s50, -2, s35
	s_and_b32 s50, s54, s50
	s_cmp_gt_i32 s35, 30
	s_cselect_b32 s50, 0, s50
	s_ff1_i32_b32 s51, s50
	s_cmp_eq_u32 s50, 0
	s_cselect_b32 s52, 1, 0
	s_cselect_b32 s51, s0, s51
	s_branch .Ln2_t_next
.Ln2_t_win:
	s_add_i32 s51, s35, 1
	s_cmp_lt_i32 s35, s76
	s_cselect_b32 s52, 1, 2
	s_cselect_b32 s51, s51, 0
.Ln2_t_next:
	s_lshl_b32 s50, s51, 6
	s_add_i32 s53, s50, s88
	s_mul_i32 s53, s53, s97
	s_movk_i32 s62, 0x2400
	s_cmp_eq_u32 s52, 0
	s_cselect_b32 s62, 0x2200, s62
	s_add_i32 s53, s53, s62
	s_add_i32 s53, s53, s84
	s_add_u32 s58, s90, s53
	s_addc_u32 s59, s91, 0
	s_lshl_b32 s62, s52, 22
	s_lshl_b32 s50, s50, 1
	s_add_i32 s62, s62, s50
	s_add_u32 s60, s56, s62
	s_addc_u32 s61, s57, 0
	s_lshl_b32 s53, s35, 6
	s_sub_i32 s50, 31, s35
	s_barrier
	s_waitcnt vmcnt(1)
	ds_write_b128 v136, v[16:19]
	s_waitcnt vmcnt(0)
	ds_write_b128 v138, v[20:23] offset:18432
	v_mov_b32_e32 v141, s52
	v_mov_b32_e32 v142, s51
	v_subrev_u32_e32 v88, s53, v126
	s_cmp_eq_u32 s34, 0
	s_cbranch_scc1 .Ln2_t_sel
	v_subrev_u32_e32 v97, s53, v134
	v_max_i32_e32 v97, 0, v97
	s_branch .Ln2_t_k
.Ln2_t_sel:
	v_lshlrev_b32_e32 v97, s50, v132
	v_cmp_gt_i32_e32 vcc, 0, v97
	v_mov_b32_e32 v97, 0
	s_nop 0
	v_cndmask_b32_e32 v88, -1, v88, vcc
.Ln2_t_k:
	s_waitcnt lgkmcnt(0)
	s_cmp_gt_u32 s52, 1
	s_cbranch_scc1 .Ln2_t_noload
	global_load_dwordx4 v[16:19], v183, s[58:59]
	global_load_dwordx4 v[20:23], v163, s[60:61]
; __device__ __forceinline__ f32x4 mfma16(bf16x8 a, bf16x8 b, f32x4 c) { return __builtin_amdgcn_mfma_f32_16x16x32_bf16(a, b, c, 0, 0, 0); }
; __device__ __forceinline__ void nsa_block_step(const bf16_t* Ks, const bf16_t* VT, const bf16x8 (&qf)[2][2], f32x4 (&O)[2][4], float (&m)[2], float (&l)[2],
;                                                int klo, int khi, int r, int q) {
;     f32x4 s[2][4];
; #pragma unroll
;     for (int x = 0; x < 2; x++)
; #pragma unroll
;         for (int kt = 0; kt < 4; kt++) s[x][kt] = (f32x4){0.f, 0.f, 0.f, 0.f};
; #pragma unroll
;     for (int kt = 0; kt < 4; kt++)
; #pragma unroll
;         for (int ks = 0; ks < 2; ks++) {
;             const bf16x8 kf = ld_frag(Ks + (kt * 16 + r) * 64 + (((ks * 4 + q) ^ (r & 7)) * 8));
; #pragma unroll
;             for (int x = 0; x < 2; x++) s[x][kt] = mfma16(kf, qf[x][ks], s[x][kt]);
;         }
;     if (!__all((klo <= 0) && (khi >= 63))) {
;         const int a = 4 * q - klo;
;         const unsigned range = (unsigned)(khi - klo);
;         const bool any = khi >= klo;
; #pragma unroll
;         for (int kt = 0; kt < 4; kt++)
; #pragma unroll
;             for (int j = 0; j < 4; j++) {
;                 const bool valid = any && ((unsigned)(kt * 16 + j + a) <= range);
; #pragma unroll
;                 for (int x = 0; x < 2; x++) s[x][kt][j] = valid ? s[x][kt][j] : -3.0e38f;
;             }
;     }
.Ln2_t_noload:
	s_barrier
	v_cmp_eq_u32_e32 vcc, 0, v97
	v_cmp_lt_i32_e64 s[6:7], 62, v88
	v_cmp_lt_i32_e64 s[48:49], v88, v97
	ds_read_b128 v[56:59], v137
	ds_read_b128 v[60:63], v137 offset:2048
	s_and_b64 s[6:7], vcc, s[6:7]
	s_or_b64 s[46:47], s[6:7], s[48:49]
	s_cmp_eq_u64 s[46:47], exec
	s_cselect_b64 s[48:49], s[48:49], 0
	v_cndmask_b32_e64 v168, v176, v123, s[48:49]
	v_cndmask_b32_e64 v169, v176, v123, s[48:49]
	v_cndmask_b32_e64 v170, v176, v123, s[48:49]
	v_cndmask_b32_e64 v171, v176, v123, s[48:49]
	v_cndmask_b32_e64 v172, v177, v123, s[48:49]
	v_cndmask_b32_e64 v173, v177, v123, s[48:49]
	v_cndmask_b32_e64 v174, v177, v123, s[48:49]
	v_cndmask_b32_e64 v175, v177, v123, s[48:49]
	ds_read_b128 v[68:71], v139
	ds_read_b128 v[76:79], v139 offset:2048
	s_waitcnt lgkmcnt(3)
	v_mfma_f32_16x16x32_bf16 v[64:67], v[56:59], v[0:3], v[168:171]
	v_mfma_f32_16x16x32_bf16 v[56:59], v[56:59], v[8:11], v[172:175]
	s_waitcnt lgkmcnt(1)
	v_mfma_f32_16x16x32_bf16 v[80:83], v[68:71], v[4:7], v[64:67]
	v_mfma_f32_16x16x32_bf16 v[68:71], v[68:71], v[12:15], v[56:59]
	v_mfma_f32_16x16x32_bf16 v[56:59], v[60:63], v[0:3], v[168:171]
	v_mfma_f32_16x16x32_bf16 v[60:63], v[60:63], v[8:11], v[172:175]
	s_waitcnt lgkmcnt(0)
	v_mfma_f32_16x16x32_bf16 v[72:75], v[76:79], v[4:7], v[56:59]
	v_mfma_f32_16x16x32_bf16 v[64:67], v[76:79], v[12:15], v[60:63]
	s_nop 3
	ds_read_b128 v[56:59], v137 offset:4096
	ds_read_b128 v[76:79], v137 offset:6144
	ds_read_b128 v[104:107], v139 offset:4096
	ds_read_b128 v[108:111], v139 offset:6144
	s_waitcnt lgkmcnt(3)
	v_mfma_f32_16x16x32_bf16 v[60:63], v[56:59], v[0:3], v[168:171]
	v_mfma_f32_16x16x32_bf16 v[56:59], v[56:59], v[8:11], v[172:175]
	s_waitcnt lgkmcnt(1)
	v_mfma_f32_16x16x32_bf16 v[84:87], v[104:107], v[4:7], v[60:63]
	v_mfma_f32_16x16x32_bf16 v[60:63], v[104:107], v[12:15], v[56:59]
	v_mfma_f32_16x16x32_bf16 v[56:59], v[76:79], v[0:3], v[168:171]
	v_mfma_f32_16x16x32_bf16 v[104:107], v[76:79], v[8:11], v[172:175]
	s_waitcnt lgkmcnt(0)
	v_mfma_f32_16x16x32_bf16 v[76:79], v[108:111], v[4:7], v[56:59]
	v_mfma_f32_16x16x32_bf16 v[56:59], v[108:111], v[12:15], v[104:107]
	s_cmp_eq_u64 s[46:47], exec
	s_cbranch_scc1 .LBB0_628
	v_min_i32_e32 v88, 63, v88
	v_sub_u32_e32 v104, v88, v97
	v_cmp_ge_i32_e32 vcc, v88, v97
	v_sub_u32_e32 v88, v129, v97
	v_cmp_le_u32_e64 s[6:7], v88, v104
	s_and_b64 s[6:7], vcc, s[6:7]
	v_add_u32_e32 v97, 1, v88
	v_cndmask_b32_e64 v80, v123, v80, s[6:7]
	v_cndmask_b32_e64 v68, v123, v68, s[6:7]
	v_cmp_le_u32_e64 s[6:7], v97, v104
	s_and_b64 s[6:7], vcc, s[6:7]
	v_add_u32_e32 v97, 2, v88
	v_cndmask_b32_e64 v81, v123, v81, s[6:7]
	v_cndmask_b32_e64 v69, v123, v69, s[6:7]
	v_cmp_le_u32_e64 s[6:7], v97, v104
	s_and_b64 s[6:7], vcc, s[6:7]
	v_add_u32_e32 v97, 3, v88
	v_cndmask_b32_e64 v82, v123, v82, s[6:7]
	v_cndmask_b32_e64 v70, v123, v70, s[6:7]
	v_cmp_le_u32_e64 s[6:7], v97, v104
	s_and_b64 s[6:7], vcc, s[6:7]
	v_add_u32_e32 v97, 16, v88
	v_cndmask_b32_e64 v83, v123, v83, s[6:7]
	v_cndmask_b32_e64 v71, v123, v71, s[6:7]
	v_cmp_le_u32_e64 s[6:7], v97, v104
	s_and_b64 s[6:7], vcc, s[6:7]
	v_add_u32_e32 v97, 17, v88
	v_cndmask_b32_e64 v72, v123, v72, s[6:7]
	v_cndmask_b32_e64 v64, v123, v64, s[6:7]
	v_cmp_le_u32_e64 s[6:7], v97, v104
	s_and_b64 s[6:7], vcc, s[6:7]
	v_add_u32_e32 v97, 18, v88
	v_cndmask_b32_e64 v73, v123, v73, s[6:7]
	v_cndmask_b32_e64 v65, v123, v65, s[6:7]
	v_cmp_le_u32_e64 s[6:7], v97, v104
	s_and_b64 s[6:7], vcc, s[6:7]
	v_add_u32_e32 v97, 19, v88
	v_cndmask_b32_e64 v74, v123, v74, s[6:7]
	v_cndmask_b32_e64 v66, v123, v66, s[6:7]
	v_cmp_le_u32_e64 s[6:7], v97, v104
	s_and_b64 s[6:7], vcc, s[6:7]
	v_add_u32_e32 v97, 32, v88
	v_cndmask_b32_e64 v75, v123, v75, s[6:7]
	v_cndmask_b32_e64 v67, v123, v67, s[6:7]
	v_cmp_le_u32_e64 s[6:7], v97, v104
	s_and_b64 s[6:7], vcc, s[6:7]
	v_add_u32_e32 v97, 33, v88
	v_cndmask_b32_e64 v84, v123, v84, s[6:7]
	v_cndmask_b32_e64 v60, v123, v60, s[6:7]
	v_cmp_le_u32_e64 s[6:7], v97, v104
	s_and_b64 s[6:7], vcc, s[6:7]
	v_add_u32_e32 v97, 34, v88
	v_cndmask_b32_e64 v85, v123, v85, s[6:7]
	v_cndmask_b32_e64 v61, v123, v61, s[6:7]
	v_cmp_le_u32_e64 s[6:7], v97, v104
	s_and_b64 s[6:7], vcc, s[6:7]
	v_add_u32_e32 v97, 35, v88
	v_cndmask_b32_e64 v86, v123, v86, s[6:7]
	v_cndmask_b32_e64 v62, v123, v62, s[6:7]
	v_cmp_le_u32_e64 s[6:7], v97, v104
	s_and_b64 s[6:7], vcc, s[6:7]
	v_add_u32_e32 v97, 48, v88
	v_cndmask_b32_e64 v87, v123, v87, s[6:7]
	v_cndmask_b32_e64 v63, v123, v63, s[6:7]
	v_cmp_le_u32_e64 s[6:7], v97, v104
	s_and_b64 s[6:7], vcc, s[6:7]
	v_add_u32_e32 v97, 49, v88
	v_cndmask_b32_e64 v76, v123, v76, s[6:7]
	v_cndmask_b32_e64 v56, v123, v56, s[6:7]
	v_cmp_le_u32_e64 s[6:7], v97, v104
	s_and_b64 s[6:7], vcc, s[6:7]
	v_add_u32_e32 v97, 50, v88
	v_cndmask_b32_e64 v77, v123, v77, s[6:7]
	v_cndmask_b32_e64 v57, v123, v57, s[6:7]
	v_cmp_le_u32_e64 s[6:7], v97, v104
	s_and_b64 s[6:7], vcc, s[6:7]
	v_add_u32_e32 v88, 51, v88
	v_cndmask_b32_e64 v78, v123, v78, s[6:7]
	v_cndmask_b32_e64 v58, v123, v58, s[6:7]
	v_cmp_le_u32_e64 s[6:7], v88, v104
	s_and_b64 vcc, vcc, s[6:7]
	v_cndmask_b32_e32 v79, v123, v79, vcc
	v_cndmask_b32_e32 v59, v123, v59, vcc

; __device__ void phaseG3_task(const Params& p, int task, char* lds, bf16_t* ydst, int ystride) {
;     const int tid = TIDX, lane = tid & 63, wave = tid >> 6, r = lane & 15, q = lane >> 4;
;     const int c = task & 31, h = (task >> 5) & 3, b = task >> 7;
;     const int tok0 = b * SEQ + c * 64;
;     bf16_t* Z = (bf16_t*)(p.ws + OFF_Z);
; __device__ __forceinline__ void nsa_block_step(const bf16_t* Ks, const bf16_t* VT, const bf16x8 (&qf)[2][2], f32x4 (&O)[2][4], float (&m)[2], float (&l)[2],
;                                                int klo, int khi, int r, int q) {
;     ...
;     bf16x8 pbv[2][2];
; #pragma unroll
;     for (int x = 0; x < 2; x++) {
;         float mx = fmaxf(fmaxf(fmaxf(s[x][0][0], s[x][0][1]), fmaxf(s[x][0][2], s[x][0][3])), fmaxf(fmaxf(s[x][1][0], s[x][1][1]), fmaxf(s[x][1][2], s[x][1][3])));
;         mx = fmaxf(mx, fmaxf(fmaxf(fmaxf(s[x][2][0], s[x][2][1]), fmaxf(s[x][2][2], s[x][2][3])), fmaxf(fmaxf(s[x][3][0], s[x][3][1]), fmaxf(s[x][3][2], s[x][3][3]))));
;         mx = xrow_max(mx);
;         const float mnew = fmaxf(m[x], mx);
;         const float alpha = exp2f_(m[x] - mnew);
;         m[x] = mnew;
;         float ls = 0.f;
; #pragma unroll
;         for (int kt = 0; kt < 4; kt++)
; #pragma unroll
;             for (int j = 0; j < 4; j++) { const float pv = exp2f_(s[x][kt][j] - mnew); s[x][kt][j] = pv; ls += pv; }
;         l[x] = l[x] * alpha + ls;
; #pragma unroll
;         for (int dt = 0; dt < 4; dt++) O[x][dt] *= alpha;
; #pragma unroll
;         for (int s2 = 0; s2 < 2; s2++) {
;             const u32x4 t4 = {pack2(s[x][2 * s2][0], s[x][2 * s2][1]), pack2(s[x][2 * s2][2], s[x][2 * s2][3]),
;                               pack2(s[x][2 * s2 + 1][0], s[x][2 * s2 + 1][1]), pack2(s[x][2 * s2 + 1][2], s[x][2 * s2 + 1][3])};
;             pbv[x][s2] = __builtin_bit_cast(bf16x8, t4);
;         }
;     }
; #pragma unroll
;     for (int s2 = 0; s2 < 2; s2++)
; #pragma unroll
;         for (int dt = 0; dt < 4; dt++) {
;             const u32x2 lo = *(const u32x2*)(VT + (dt * 16 + r) * 72 + (2 * s2) * 16 + 4 * q);
;             const u32x2 hi = *(const u32x2*)(VT + (dt * 16 + r) * 72 + (2 * s2 + 1) * 16 + 4 * q);
;             const bf16x8 va = mk_frag(lo, hi);
; #pragma unroll
;             for (int x = 0; x < 2; x++) O[x][dt] = mfma16(va, pbv[x][s2], O[x][dt]);
;         }
.Ln2_fast:
	v_add_u32_e32 v216, 0x4800, v135
	v_add_u32_e32 v217, 0x5000, v135
	v_add_u32_e32 v218, 0x5800, v135
	v_add_u32_e32 v219, 0x6000, v135
	ds_read2_b64 v[200:203], v216 offset1:4
	ds_read2_b64 v[204:207], v217 offset0:32 offset1:36
	ds_read2_b64 v[208:211], v218 offset0:64 offset1:68
	ds_read2_b64 v[212:215], v219 offset0:96 offset1:100
	v_exp_f32_e32 v80, v80
	v_exp_f32_e32 v81, v81
	v_exp_f32_e32 v82, v82
	v_exp_f32_e32 v83, v83
	v_exp_f32_e32 v72, v72
	v_exp_f32_e32 v73, v73
	v_exp_f32_e32 v74, v74
	v_exp_f32_e32 v75, v75
	ds_read2_b64 v[224:227], v216 offset0:8 offset1:12
	ds_read2_b64 v[228:231], v217 offset0:40 offset1:44
	v_exp_f32_e32 v68, v68
	v_exp_f32_e32 v69, v69
	v_exp_f32_e32 v70, v70
	v_exp_f32_e32 v71, v71
	v_exp_f32_e32 v64, v64
	v_exp_f32_e32 v65, v65
	v_exp_f32_e32 v66, v66
	v_exp_f32_e32 v67, v67
	ds_read2_b64 v[232:235], v218 offset0:72 offset1:76
	ds_read2_b64 v[236:239], v219 offset0:104 offset1:108
	v_cvt_pk_bf16_f32 v184, v80, v81
	v_cvt_pk_bf16_f32 v185, v82, v83
	v_cvt_pk_bf16_f32 v186, v72, v73
	v_cvt_pk_bf16_f32 v187, v74, v75
	v_cvt_pk_bf16_f32 v192, v68, v69
	v_cvt_pk_bf16_f32 v193, v70, v71
	v_cvt_pk_bf16_f32 v194, v64, v65
	v_cvt_pk_bf16_f32 v195, v66, v67
	v_exp_f32_e32 v84, v84
	v_exp_f32_e32 v85, v85
	s_waitcnt lgkmcnt(7)
	v_mfma_f32_16x16x32_bf16 v[52:55], v[200:203], v[184:187], v[52:55]
	v_exp_f32_e32 v86, v86
	v_exp_f32_e32 v87, v87
	v_mfma_f32_16x16x32_bf16 v[36:39], v[200:203], v[192:195], v[36:39]
	v_exp_f32_e32 v76, v76
	v_exp_f32_e32 v77, v77
	s_waitcnt lgkmcnt(6)
	v_mfma_f32_16x16x32_bf16 v[48:51], v[204:207], v[184:187], v[48:51]
	v_exp_f32_e32 v78, v78
	v_exp_f32_e32 v79, v79
	v_mfma_f32_16x16x32_bf16 v[32:35], v[204:207], v[192:195], v[32:35]
	v_exp_f32_e32 v60, v60
	v_exp_f32_e32 v61, v61
	s_waitcnt lgkmcnt(5)
	v_mfma_f32_16x16x32_bf16 v[44:47], v[208:211], v[184:187], v[44:47]
	v_exp_f32_e32 v62, v62
	v_exp_f32_e32 v63, v63
	v_mfma_f32_16x16x32_bf16 v[28:31], v[208:211], v[192:195], v[28:31]
	v_exp_f32_e32 v56, v56
	v_exp_f32_e32 v57, v57
	s_waitcnt lgkmcnt(4)
	v_mfma_f32_16x16x32_bf16 v[40:43], v[212:215], v[184:187], v[40:43]
	v_exp_f32_e32 v58, v58
	v_exp_f32_e32 v59, v59
	v_mfma_f32_16x16x32_bf16 v[24:27], v[212:215], v[192:195], v[24:27]
	v_cvt_pk_bf16_f32 v188, v84, v85
	v_cvt_pk_bf16_f32 v189, v86, v87
	v_cvt_pk_bf16_f32 v190, v76, v77
	v_cvt_pk_bf16_f32 v191, v78, v79
	v_cvt_pk_bf16_f32 v196, v60, v61
	v_cvt_pk_bf16_f32 v197, v62, v63
	v_cvt_pk_bf16_f32 v198, v56, v57
	v_cvt_pk_bf16_f32 v199, v58, v59
	v_add_f32_e32 v221, v80, v81
	v_add_f32_e32 v220, v68, v69
	s_waitcnt lgkmcnt(3)
	v_mfma_f32_16x16x32_bf16 v[52:55], v[224:227], v[188:191], v[52:55]
	v_add_f32_e32 v221, v221, v82
	v_add_f32_e32 v220, v220, v70
	v_mfma_f32_16x16x32_bf16 v[36:39], v[224:227], v[196:199], v[36:39]
	v_add_f32_e32 v221, v221, v83
	v_add_f32_e32 v220, v220, v71
	s_waitcnt lgkmcnt(2)
	v_mfma_f32_16x16x32_bf16 v[48:51], v[228:231], v[188:191], v[48:51]
	v_add_f32_e32 v221, v221, v72
	v_add_f32_e32 v220, v220, v64
	v_mfma_f32_16x16x32_bf16 v[32:35], v[228:231], v[196:199], v[32:35]
	v_add_f32_e32 v221, v221, v73
	v_add_f32_e32 v220, v220, v65
	s_waitcnt lgkmcnt(1)
	v_mfma_f32_16x16x32_bf16 v[44:47], v[232:235], v[188:191], v[44:47]
	v_add_f32_e32 v221, v221, v74
	v_add_f32_e32 v220, v220, v66
	v_mfma_f32_16x16x32_bf16 v[28:31], v[232:235], v[196:199], v[28:31]
	v_add_f32_e32 v221, v221, v75
	v_add_f32_e32 v220, v220, v67
	s_waitcnt lgkmcnt(0)
	v_mfma_f32_16x16x32_bf16 v[40:43], v[236:239], v[188:191], v[40:43]
	v_add_f32_e32 v221, v221, v84
	v_add_f32_e32 v220, v220, v60
	v_mfma_f32_16x16x32_bf16 v[24:27], v[236:239], v[196:199], v[24:27]
	v_add_f32_e32 v221, v221, v85
	v_add_f32_e32 v220, v220, v61
	v_add_f32_e32 v221, v221, v86
	v_add_f32_e32 v220, v220, v62
	v_add_f32_e32 v221, v221, v87
	v_add_f32_e32 v220, v220, v63
	v_add_f32_e32 v221, v221, v76
	v_add_f32_e32 v220, v220, v56
	v_add_f32_e32 v221, v221, v77
	v_add_f32_e32 v220, v220, v57
	v_add_f32_e32 v221, v221, v78
	v_add_f32_e32 v220, v220, v58
	v_add_f32_e32 v221, v221, v79
	v_add_f32_e32 v220, v220, v59
	v_cmp_ne_u32_e32 vcc, v141, v143
	v_mov_b32_e32 v88, v103
	v_mov_b32_e32 v97, v102
	v_pk_add_f32 v[100:101], v[100:101], v[220:221]
	s_branch .Ln2_tail
.LBB0_632:
	s_load_dwordx2 s[72:73], s[80:81], 0xe0
	v_readfirstlane_b32 s0, v158
	s_lshr_b32 s0, s0, 8
	v_readlane_b32 s77, v222, 11
	s_add_i32 s1, s0, s77
	s_cmpk_gt_i32 s1, 0x3ff
	v_readlane_b32 s75, v222, 10
	v_readlane_b32 s76, v222, 9
	s_cbranch_scc1 .LBB0_649
	v_readlane_b32 s5, v222, 0
	s_lshl_b32 s3, s5, 5
	s_lshl_b32 s4, s0, 4
	s_add_i32 s3, s3, s4
	s_lshl_b32 s4, s5, 7
	s_lshl_b32 s5, s0, 6
	s_add_i32 s2, s33, 0x11800
	s_waitcnt lgkmcnt(0)
	s_lshl_b32 s8, s72, 1
	s_lshl_b32 s21, s72, 5
	s_add_i32 s25, s4, s5
	s_lshl_b32 s27, s72, 7
	s_ashr_i32 s5, s77, 31
	s_add_u32 s4, s0, s77
	s_addc_u32 s5, 0, s5
	s_lshl_b64 s[6:7], s[4:5], 15
	s_add_u32 s12, s6, 0x3c00000
	s_addc_u32 s13, s7, 0
	s_ashr_i32 s9, s8, 31
	s_mov_b32 s11, 0
	s_lshl_b64 s[14:15], s[8:9], 15
	s_lshl_b64 s[16:17], s[4:5], 16
	s_lshl_b64 s[18:19], s[8:9], 16
	v_mov_b32_e32 v65, 0
	s_movk_i32 s9, 0x1000
	s_movk_i32 s36, 0x2000
	s_movk_i32 s37, 0x3000
	s_movk_i32 s38, 0x4000
	s_movk_i32 s39, 0x6000
	s_movk_i32 s40, 0x7000
	s_movk_i32 s41, 0x2700
	s_mov_b32 s20, 0x3db504f3
	s_movk_i32 s42, 0x110
	s_movk_i32 s43, 0x7f
	s_mov_b64 s[22:23], 0x1000
	s_mov_b32 s24, 0x3b800000
	s_mov_b32 s26, 0x358637bd
	s_mov_b32 s44, 0x800000
	v_mov_b32_e32 v76, 4
	v_mov_b32_e32 v77, 63
	s_branch .LBB0_635
